# P0 RMSNorm1 row loop: real next-row prefetch (gamma resident in registers, one counted vmcnt(4) at the loop top instead of draining the prefetch and four gamma reloads every iteration)
# baseline (speedup 1.0000x reference)
.LBB0_8:
	s_or_b64 exec, exec, s[2:3]
	v_lshrrev_b32_e32 v1, 6, v0
	v_lshl_add_u32 v36, s10, 3, v1
	s_movk_i32 s11, 0x4000
	s_add_u32 s6, s96, 0x188
	v_cmp_gt_i32_e32 vcc, s11, v36
	s_addc_u32 s7, s97, 0
	s_and_saveexec_b64 s[8:9], vcc
	s_cbranch_execz .LBB0_13
	v_ashrrev_i32_e32 v37, 31, v36
	v_lshlrev_b32_e32 v1, 2, v0
	s_waitcnt lgkmcnt(2)
	v_lshlrev_b64 v[2:3], 12, v[36:37]
	v_and_b32_e32 v20, 0xfc, v1
	v_lshl_add_u64 v[2:3], s[52:53], 0, v[2:3]
	v_lshlrev_b32_e32 v18, 2, v20
	v_mov_b32_e32 v19, 0
	v_lshl_add_u64 v[2:3], v[2:3], 0, v[18:19]
	s_waitcnt lgkmcnt(0)
	v_mbcnt_lo_u32_b32 v1, -1, 0
	v_mbcnt_hi_u32_b32 v21, -1, v1
	v_and_b32_e32 v1, 64, v21
	v_add_u32_e32 v22, 64, v1
	v_xor_b32_e32 v1, 32, v21
	v_cmp_lt_i32_e32 vcc, v1, v22
	v_xor_b32_e32 v23, 16, v21
	s_load_dword s0, s[6:7], 0x0
	v_cndmask_b32_e32 v1, v21, v1, vcc
	v_cmp_lt_i32_e32 vcc, v23, v22
	v_lshl_add_u64 v[34:35], s[54:55], 0, v[18:19]
	v_lshl_add_u64 v[38:39], s[52:53], 0, v[18:19]
	v_cndmask_b32_e32 v23, v21, v23, vcc
	v_lshlrev_b32_e32 v44, 2, v23
	v_xor_b32_e32 v23, 8, v21
	v_cmp_lt_i32_e32 vcc, v23, v22
	v_lshlrev_b32_e32 v18, 1, v20
	s_waitcnt lgkmcnt(0)
	s_lshl_b32 s33, s0, 3
	v_cndmask_b32_e32 v23, v21, v23, vcc
	v_lshlrev_b32_e32 v45, 2, v23
	v_xor_b32_e32 v23, 4, v21
	v_cmp_lt_i32_e32 vcc, v23, v22
	v_lshlrev_b32_e32 v1, 2, v1
	v_lshl_add_u64 v[40:41], s[48:49], 0, v[18:19]
	v_cndmask_b32_e32 v23, v21, v23, vcc
	v_lshlrev_b32_e32 v46, 2, v23
	v_xor_b32_e32 v23, 2, v21
	v_cmp_lt_i32_e32 vcc, v23, v22
	s_mov_b64 s[28:29], 0
	s_movk_i32 s34, 0x3fff
	v_cndmask_b32_e32 v23, v21, v23, vcc
	v_lshlrev_b32_e32 v47, 2, v23
	v_xor_b32_e32 v23, 1, v21
	v_cmp_lt_i32_e32 vcc, v23, v22
	v_mov_b32_e32 v49, 0x358637bd
	s_mov_b32 s35, 0x800000
	v_cndmask_b32_e32 v21, v21, v23, vcc
	v_lshlrev_b32_e32 v48, 2, v21
	global_load_dwordx4 v[80:83], v[34:35], off
	global_load_dwordx4 v[84:87], v[34:35], off offset:1024
	global_load_dwordx4 v[88:91], v[34:35], off offset:2048
	global_load_dwordx4 v[92:95], v[34:35], off offset:3072
	global_load_dwordx4 v[18:21], v[2:3], off
	global_load_dwordx4 v[22:25], v[2:3], off offset:1024
	global_load_dwordx4 v[26:29], v[2:3], off offset:2048
	global_load_dwordx4 v[30:33], v[2:3], off offset:3072
	s_waitcnt vmcnt(0)
	s_branch .LBB0_11
.LBB0_11:
	s_waitcnt vmcnt(4)
	v_mov_b64_e32 v[14:15], v[18:19]
	v_mov_b64_e32 v[16:17], v[20:21]
	v_mov_b64_e32 v[10:11], v[22:23]
	v_mov_b64_e32 v[12:13], v[24:25]
	v_mov_b64_e32 v[6:7], v[26:27]
	v_mov_b64_e32 v[8:9], v[28:29]
	v_mov_b64_e32 v[2:3], v[30:31]
	v_mov_b64_e32 v[4:5], v[32:33]
	v_add_u32_e32 v42, s33, v36
	v_cmp_gt_i32_e64 s[2:3], s11, v42
	v_cmp_lt_i32_e32 vcc, s34, v42
	s_and_saveexec_b64 s[30:31], s[2:3]
	s_cbranch_execz .LBB0_10
	v_ashrrev_i32_e32 v43, 31, v42
	v_lshlrev_b64 v[18:19], 12, v[42:43]
	v_lshl_add_u64 v[30:31], v[38:39], 0, v[18:19]
	global_load_dwordx4 v[18:21], v[30:31], off
	global_load_dwordx4 v[22:25], v[30:31], off offset:1024
	global_load_dwordx4 v[26:29], v[30:31], off offset:2048
	s_nop 0
	global_load_dwordx4 v[30:33], v[30:31], off offset:3072
.LBB0_10:
	s_or_b64 exec, exec, s[30:31]
	v_mov_b32_e32 v54, v10
	v_mov_b32_e32 v55, v14
	v_mov_b32_e32 v56, v11
	v_mov_b32_e32 v57, v15
	v_mov_b32_e32 v62, v2
	v_mov_b32_e32 v63, v6
	v_pk_mul_f32 v[54:55], v[54:55], v[54:55]
	v_mov_b32_e32 v58, v12
	v_mov_b32_e32 v59, v16
	v_mov_b32_e32 v64, v3
	v_mov_b32_e32 v65, v7
	v_pk_mul_f32 v[62:63], v[62:63], v[62:63]
	v_pk_fma_f32 v[54:55], v[56:57], v[56:57], v[54:55]
	v_mov_b32_e32 v60, v13
	v_mov_b32_e32 v61, v17
	v_mov_b32_e32 v66, v4
	v_mov_b32_e32 v67, v8
	v_pk_fma_f32 v[56:57], v[64:65], v[64:65], v[62:63]
	v_pk_fma_f32 v[54:55], v[58:59], v[58:59], v[54:55]
	v_mov_b32_e32 v68, v5
	v_mov_b32_e32 v69, v9
	v_pk_fma_f32 v[56:57], v[66:67], v[66:67], v[56:57]
	v_pk_fma_f32 v[54:55], v[60:61], v[60:61], v[54:55]
	v_pk_fma_f32 v[56:57], v[68:69], v[68:69], v[56:57]
	v_add_f32_e32 v37, v54, v55
	v_add_f32_e32 v37, v57, v37
	v_add_f32_e32 v37, v56, v37
	ds_bpermute_b32 v43, v1, v37
	s_waitcnt lgkmcnt(0)
	v_add_f32_e32 v37, v37, v43
	ds_bpermute_b32 v43, v44, v37
	s_waitcnt lgkmcnt(0)
	v_add_f32_e32 v37, v37, v43
	ds_bpermute_b32 v43, v45, v37
	s_waitcnt lgkmcnt(0)
	v_add_f32_e32 v37, v37, v43
	ds_bpermute_b32 v43, v46, v37
	s_waitcnt lgkmcnt(0)
	v_add_f32_e32 v37, v37, v43
	ds_bpermute_b32 v43, v47, v37
	s_waitcnt lgkmcnt(0)
	v_add_f32_e32 v37, v37, v43
	ds_bpermute_b32 v43, v48, v37
	s_waitcnt lgkmcnt(0)
	v_add_f32_e32 v37, v37, v43
	v_fmamk_f32 v37, v37, 0x3a800000, v49
	v_mul_f32_e32 v43, 0x4b800000, v37
	v_cmp_gt_f32_e64 s[2:3], s35, v37
	s_nop 1
	v_cndmask_b32_e64 v37, v37, v43, s[2:3]
	v_rsq_f32_e32 v43, v37
	v_ashrrev_i32_e32 v37, 31, v36
	v_lshlrev_b64 v[36:37], 11, v[36:37]
	v_lshl_add_u64 v[54:55], v[40:41], 0, v[36:37]
	v_mul_f32_e32 v36, 0x45800000, v43
	v_cndmask_b32_e64 v56, v43, v36, s[2:3]
	v_pk_mul_f32 v[14:15], v[14:15], v[56:57] op_sel_hi:[1,0]
	v_pk_mul_f32 v[16:17], v[16:17], v[56:57] op_sel_hi:[1,0]
	v_pk_mul_f32 v[10:11], v[10:11], v[56:57] op_sel_hi:[1,0]
	v_pk_mul_f32 v[12:13], v[12:13], v[56:57] op_sel_hi:[1,0]
	v_pk_mul_f32 v[14:15], v[80:81], v[14:15]
	v_pk_mul_f32 v[16:17], v[82:83], v[16:17]
	v_cvt_pk_bf16_f32 v14, v14, v15
	v_cvt_pk_bf16_f32 v15, v16, v17
	global_store_dwordx2 v[54:55], v[14:15], off
	v_pk_mul_f32 v[6:7], v[6:7], v[56:57] op_sel_hi:[1,0]
	v_pk_mul_f32 v[8:9], v[8:9], v[56:57] op_sel_hi:[1,0]
	v_mov_b32_e32 v36, v42
	v_pk_mul_f32 v[2:3], v[2:3], v[56:57] op_sel_hi:[1,0]
	v_pk_mul_f32 v[42:43], v[4:5], v[56:57] op_sel_hi:[1,0]
	s_and_b64 s[2:3], exec, vcc
	s_or_b64 s[28:29], s[2:3], s[28:29]
	v_pk_mul_f32 v[10:11], v[84:85], v[10:11]
	v_pk_mul_f32 v[12:13], v[86:87], v[12:13]
	v_cvt_pk_bf16_f32 v10, v10, v11
	v_cvt_pk_bf16_f32 v11, v12, v13
	global_store_dwordx2 v[54:55], v[10:11], off offset:512
	v_pk_mul_f32 v[6:7], v[6:7], v[88:89]
	v_pk_mul_f32 v[8:9], v[8:9], v[90:91]
	v_cvt_pk_bf16_f32 v6, v6, v7
	v_cvt_pk_bf16_f32 v7, v8, v9
	global_store_dwordx2 v[54:55], v[6:7], off offset:1024
	v_pk_mul_f32 v[2:3], v[2:3], v[92:93]
	v_pk_mul_f32 v[42:43], v[42:43], v[94:95]
	v_cvt_pk_bf16_f32 v2, v2, v3
	v_cvt_pk_bf16_f32 v3, v42, v43
	global_store_dwordx2 v[54:55], v[2:3], off offset:1536
	s_andn2_b64 exec, exec, s[28:29]
	s_cbranch_execnz .LBB0_11
